# v132 + nt hint on A-operand (U/H) LDS-DMA loads of out-proj/ff2 GEMM K-loop
# baseline (speedup 1.0000x reference)
.LBB0_516:
	s_add_i32 s50, s42, 2
	s_add_u32 s51, s40, 0x80
	s_addc_u32 s43, s41, 0
	s_add_i32 s94, 0, 0x10000
	s_cmp_eq_u32 s44, s42
	s_cselect_b32 s43, s35, s43
	s_cselect_b32 s42, s34, s51
	v_add_u32_e32 v0, s94, v142
	s_cselect_b32 s93, s37, s31
	s_cselect_b32 s92, s36, s25
	s_add_i32 s51, 0, 0x14000
	ds_read_b128 v[138:141], v0
	ds_read_b128 v[146:149], v0 offset:1024
	ds_read_b128 v[150:153], v0 offset:2048
	ds_read_b128 v[168:171], v0 offset:3072
	v_add_u32_e32 v0, s51, v142
	ds_read_b128 v[172:175], v0
	ds_read_b128 v[176:179], v0 offset:1024
	ds_read_b128 v[180:183], v0 offset:2048
	ds_read_b128 v[184:187], v0 offset:3072
	v_lshl_add_u64 v[216:217], s[40:41], 0, v[134:135]
	s_add_i32 m0, s11, 0xc000
	ds_read_b128 v[188:191], v145
	ds_read_b128 v[192:195], v145 offset:1024
	ds_read_b128 v[196:199], v145 offset:2048
	ds_read_b128 v[200:203], v145 offset:3072
	ds_read_b128 v[204:207], v145 offset:4096
	ds_read_b128 v[208:211], v145 offset:5120
	ds_read_b128 v[212:215], v145 offset:6144
	ds_read_b128 v[234:237], v145 offset:7168
	global_load_lds_dwordx4 v[216:217], off nt
	v_lshl_add_u64 v[216:217], s[40:41], 0, v[136:137]
	s_add_i32 m0, s11, 0xe000
	s_nop 0
	global_load_lds_dwordx4 v[216:217], off nt
	s_waitcnt vmcnt(8)
	s_waitcnt lgkmcnt(0)
	s_barrier
	s_setprio 1
	s_waitcnt lgkmcnt(0)
	v_mfma_f32_16x16x32_bf16 v[126:129], v[138:141], v[188:191], v[126:129]
	v_mfma_f32_16x16x32_bf16 v[122:125], v[150:153], v[188:191], v[122:125]
	v_mfma_f32_16x16x32_bf16 v[114:117], v[138:141], v[196:199], v[114:117]
	v_mfma_f32_16x16x32_bf16 v[106:109], v[150:153], v[196:199], v[106:109]
	v_mfma_f32_16x16x32_bf16 v[98:101], v[138:141], v[204:207], v[98:101]
	v_mfma_f32_16x16x32_bf16 v[90:93], v[150:153], v[204:207], v[90:93]
	v_mfma_f32_16x16x32_bf16 v[82:85], v[138:141], v[212:215], v[82:85]
	v_mfma_f32_16x16x32_bf16 v[74:77], v[150:153], v[212:215], v[74:77]
	v_mfma_f32_16x16x32_bf16 v[126:129], v[146:149], v[192:195], v[126:129]
	v_mfma_f32_16x16x32_bf16 v[122:125], v[168:171], v[192:195], v[122:125]
	v_mfma_f32_16x16x32_bf16 v[114:117], v[146:149], v[200:203], v[114:117]
	v_mfma_f32_16x16x32_bf16 v[106:109], v[168:171], v[200:203], v[106:109]
	v_mfma_f32_16x16x32_bf16 v[98:101], v[146:149], v[208:211], v[98:101]
	v_mfma_f32_16x16x32_bf16 v[90:93], v[168:171], v[208:211], v[90:93]
	v_mfma_f32_16x16x32_bf16 v[82:85], v[146:149], v[234:237], v[82:85]
	v_mfma_f32_16x16x32_bf16 v[74:77], v[168:171], v[234:237], v[74:77]
	s_setprio 0
	s_setprio 1
	v_mfma_f32_16x16x32_bf16 v[118:121], v[172:175], v[188:191], v[118:121]
	v_mfma_f32_16x16x32_bf16 v[110:113], v[180:183], v[188:191], v[110:113]
	v_mfma_f32_16x16x32_bf16 v[102:105], v[172:175], v[196:199], v[102:105]
	v_mfma_f32_16x16x32_bf16 v[94:97], v[180:183], v[196:199], v[94:97]
	v_mfma_f32_16x16x32_bf16 v[86:89], v[172:175], v[204:207], v[86:89]
	v_mfma_f32_16x16x32_bf16 v[78:81], v[180:183], v[204:207], v[78:81]
	v_mfma_f32_16x16x32_bf16 v[70:73], v[172:175], v[212:215], v[70:73]
	v_mfma_f32_16x16x32_bf16 v[66:69], v[180:183], v[212:215], v[66:69]
	v_mfma_f32_16x16x32_bf16 v[118:121], v[176:179], v[192:195], v[118:121]
	v_mfma_f32_16x16x32_bf16 v[110:113], v[184:187], v[192:195], v[110:113]
	v_mfma_f32_16x16x32_bf16 v[102:105], v[176:179], v[200:203], v[102:105]
	v_mfma_f32_16x16x32_bf16 v[94:97], v[184:187], v[200:203], v[94:97]
	v_mfma_f32_16x16x32_bf16 v[86:89], v[176:179], v[208:211], v[86:89]
	v_mfma_f32_16x16x32_bf16 v[78:81], v[184:187], v[208:211], v[78:81]
	v_mfma_f32_16x16x32_bf16 v[70:73], v[176:179], v[234:237], v[70:73]
	v_mfma_f32_16x16x32_bf16 v[66:69], v[184:187], v[234:237], v[66:69]
	s_setprio 0
	s_barrier
	s_add_i32 s94, s94, s9
	v_lshl_add_u64 v[216:217], s[92:93], 0, v[132:133]
	s_mov_b32 m0, s94
	ds_read_b128 v[188:191], v145 offset:16384
	ds_read_b128 v[192:195], v145 offset:17408
	ds_read_b128 v[196:199], v145 offset:18432
	ds_read_b128 v[200:203], v145 offset:19456
	ds_read_b128 v[204:207], v145 offset:20480
	ds_read_b128 v[208:211], v145 offset:21504
	ds_read_b128 v[212:215], v145 offset:22528
	ds_read_b128 v[234:237], v145 offset:23552
	global_load_lds_dwordx4 v[216:217], off
	s_add_i32 m0, s94, 0x2000
	v_lshl_add_u64 v[222:223], s[92:93], 0, v[130:131]
	s_add_u32 s92, s92, s0
	s_addc_u32 s93, s93, s1
	s_add_i32 s51, s51, s9
	global_load_lds_dwordx4 v[222:223], off
	v_lshl_add_u64 v[224:225], s[92:93], 0, v[132:133]
	s_mov_b32 m0, s51
	v_lshl_add_u64 v[226:227], s[92:93], 0, v[130:131]
	global_load_lds_dwordx4 v[224:225], off
	s_add_i32 m0, s51, 0x2000
	v_lshl_add_u64 v[238:239], s[42:43], 0, v[132:133]
	global_load_lds_dwordx4 v[226:227], off
	s_mov_b32 m0, s11
	v_lshl_add_u64 v[240:241], s[42:43], 0, v[130:131]
	global_load_lds_dwordx4 v[238:239], off nt
	s_mov_b32 m0, s12
	s_nop 0
	global_load_lds_dwordx4 v[240:241], off nt
	s_waitcnt vmcnt(8)
	s_waitcnt lgkmcnt(0)
	s_barrier
	s_setprio 1
	s_waitcnt lgkmcnt(0)
	v_mfma_f32_16x16x32_bf16 v[62:65], v[138:141], v[188:191], v[62:65]
	v_mfma_f32_16x16x32_bf16 v[58:61], v[150:153], v[188:191], v[58:61]
	v_mfma_f32_16x16x32_bf16 v[50:53], v[138:141], v[196:199], v[50:53]
	v_mfma_f32_16x16x32_bf16 v[42:45], v[150:153], v[196:199], v[42:45]
	v_mfma_f32_16x16x32_bf16 v[34:37], v[138:141], v[204:207], v[34:37]
	v_mfma_f32_16x16x32_bf16 v[26:29], v[150:153], v[204:207], v[26:29]
	v_mfma_f32_16x16x32_bf16 v[18:21], v[138:141], v[212:215], v[18:21]
	v_mfma_f32_16x16x32_bf16 v[10:13], v[150:153], v[212:215], v[10:13]
	v_mfma_f32_16x16x32_bf16 v[62:65], v[146:149], v[192:195], v[62:65]
	v_mfma_f32_16x16x32_bf16 v[58:61], v[168:171], v[192:195], v[58:61]
	v_mfma_f32_16x16x32_bf16 v[50:53], v[146:149], v[200:203], v[50:53]
	v_mfma_f32_16x16x32_bf16 v[42:45], v[168:171], v[200:203], v[42:45]
	v_mfma_f32_16x16x32_bf16 v[34:37], v[146:149], v[208:211], v[34:37]
	v_mfma_f32_16x16x32_bf16 v[26:29], v[168:171], v[208:211], v[26:29]
	v_mfma_f32_16x16x32_bf16 v[18:21], v[146:149], v[234:237], v[18:21]
	v_mfma_f32_16x16x32_bf16 v[10:13], v[168:171], v[234:237], v[10:13]
	s_setprio 0
	s_setprio 1
	v_mfma_f32_16x16x32_bf16 v[54:57], v[172:175], v[188:191], v[54:57]
	v_mfma_f32_16x16x32_bf16 v[46:49], v[180:183], v[188:191], v[46:49]
	v_mfma_f32_16x16x32_bf16 v[38:41], v[172:175], v[196:199], v[38:41]
	v_mfma_f32_16x16x32_bf16 v[30:33], v[180:183], v[196:199], v[30:33]
	v_mfma_f32_16x16x32_bf16 v[22:25], v[172:175], v[204:207], v[22:25]
	v_mfma_f32_16x16x32_bf16 v[14:17], v[180:183], v[204:207], v[14:17]
	v_mfma_f32_16x16x32_bf16 v[6:9], v[172:175], v[212:215], v[6:9]
	v_mfma_f32_16x16x32_bf16 v[2:5], v[180:183], v[212:215], v[2:5]
	v_mfma_f32_16x16x32_bf16 v[54:57], v[176:179], v[192:195], v[54:57]
	v_mfma_f32_16x16x32_bf16 v[46:49], v[184:187], v[192:195], v[46:49]
	v_mfma_f32_16x16x32_bf16 v[38:41], v[176:179], v[200:203], v[38:41]
	v_mfma_f32_16x16x32_bf16 v[30:33], v[184:187], v[200:203], v[30:33]
	v_mfma_f32_16x16x32_bf16 v[22:25], v[176:179], v[208:211], v[22:25]
	v_mfma_f32_16x16x32_bf16 v[14:17], v[184:187], v[208:211], v[14:17]
	v_mfma_f32_16x16x32_bf16 v[6:9], v[176:179], v[234:237], v[6:9]
	v_mfma_f32_16x16x32_bf16 v[2:5], v[184:187], v[234:237], v[2:5]
	s_setprio 0
	s_barrier
	s_add_i32 s51, 0, 0x18000
	v_add_u32_e32 v0, s51, v142
	s_add_i32 s92, 0, 0x1c000
	ds_read_b128 v[138:141], v0
	ds_read_b128 v[146:149], v0 offset:1024
	ds_read_b128 v[150:153], v0 offset:2048
	ds_read_b128 v[168:171], v0 offset:3072
	v_add_u32_e32 v0, s92, v142
	ds_read_b128 v[172:175], v0
	ds_read_b128 v[176:179], v0 offset:1024
	ds_read_b128 v[180:183], v0 offset:2048
	ds_read_b128 v[184:187], v0 offset:3072
	s_add_u32 s42, s42, s0
	s_addc_u32 s43, s43, s1
	s_mov_b32 m0, s13
	v_lshl_add_u64 v[242:243], s[42:43], 0, v[132:133]
	ds_read_b128 v[188:191], v145 offset:32768
	ds_read_b128 v[192:195], v145 offset:33792
	ds_read_b128 v[196:199], v145 offset:34816
	ds_read_b128 v[200:203], v145 offset:35840
	ds_read_b128 v[204:207], v145 offset:36864
	ds_read_b128 v[208:211], v145 offset:37888
	ds_read_b128 v[212:215], v145 offset:38912
	ds_read_b128 v[234:237], v145 offset:39936
	global_load_lds_dwordx4 v[242:243], off nt
	v_lshl_add_u64 v[242:243], s[42:43], 0, v[130:131]
	s_mov_b32 m0, s14
	s_nop 0
	global_load_lds_dwordx4 v[242:243], off nt
	s_waitcnt vmcnt(8)
	s_waitcnt lgkmcnt(0)
	s_barrier
	s_setprio 1
	s_waitcnt lgkmcnt(0)
	v_mfma_f32_16x16x32_bf16 v[126:129], v[138:141], v[188:191], v[126:129]
	v_mfma_f32_16x16x32_bf16 v[122:125], v[150:153], v[188:191], v[122:125]
	v_mfma_f32_16x16x32_bf16 v[114:117], v[138:141], v[196:199], v[114:117]
	v_mfma_f32_16x16x32_bf16 v[106:109], v[150:153], v[196:199], v[106:109]
	v_mfma_f32_16x16x32_bf16 v[98:101], v[138:141], v[204:207], v[98:101]
	v_mfma_f32_16x16x32_bf16 v[90:93], v[150:153], v[204:207], v[90:93]
	v_mfma_f32_16x16x32_bf16 v[82:85], v[138:141], v[212:215], v[82:85]
	v_mfma_f32_16x16x32_bf16 v[74:77], v[150:153], v[212:215], v[74:77]
	v_mfma_f32_16x16x32_bf16 v[126:129], v[146:149], v[192:195], v[126:129]
	v_mfma_f32_16x16x32_bf16 v[122:125], v[168:171], v[192:195], v[122:125]
	v_mfma_f32_16x16x32_bf16 v[114:117], v[146:149], v[200:203], v[114:117]
	v_mfma_f32_16x16x32_bf16 v[106:109], v[168:171], v[200:203], v[106:109]
	v_mfma_f32_16x16x32_bf16 v[98:101], v[146:149], v[208:211], v[98:101]
	v_mfma_f32_16x16x32_bf16 v[90:93], v[168:171], v[208:211], v[90:93]
	v_mfma_f32_16x16x32_bf16 v[82:85], v[146:149], v[234:237], v[82:85]
	v_mfma_f32_16x16x32_bf16 v[74:77], v[168:171], v[234:237], v[74:77]
	s_setprio 0
	s_setprio 1
	v_mfma_f32_16x16x32_bf16 v[118:121], v[172:175], v[188:191], v[118:121]
	v_mfma_f32_16x16x32_bf16 v[110:113], v[180:183], v[188:191], v[110:113]
	v_mfma_f32_16x16x32_bf16 v[102:105], v[172:175], v[196:199], v[102:105]
	v_mfma_f32_16x16x32_bf16 v[94:97], v[180:183], v[196:199], v[94:97]
	v_mfma_f32_16x16x32_bf16 v[86:89], v[172:175], v[204:207], v[86:89]
	v_mfma_f32_16x16x32_bf16 v[78:81], v[180:183], v[204:207], v[78:81]
	v_mfma_f32_16x16x32_bf16 v[70:73], v[172:175], v[212:215], v[70:73]
	v_mfma_f32_16x16x32_bf16 v[66:69], v[180:183], v[212:215], v[66:69]
	v_mfma_f32_16x16x32_bf16 v[118:121], v[176:179], v[192:195], v[118:121]
	v_mfma_f32_16x16x32_bf16 v[110:113], v[184:187], v[192:195], v[110:113]
	v_mfma_f32_16x16x32_bf16 v[102:105], v[176:179], v[200:203], v[102:105]
	v_mfma_f32_16x16x32_bf16 v[94:97], v[184:187], v[200:203], v[94:97]
	v_mfma_f32_16x16x32_bf16 v[86:89], v[176:179], v[208:211], v[86:89]
	v_mfma_f32_16x16x32_bf16 v[78:81], v[184:187], v[208:211], v[78:81]
	v_mfma_f32_16x16x32_bf16 v[70:73], v[176:179], v[234:237], v[70:73]
	v_mfma_f32_16x16x32_bf16 v[66:69], v[184:187], v[234:237], v[66:69]
	s_setprio 0
	s_barrier
	s_add_i32 s42, s51, s9
	v_lshl_add_u64 v[216:217], v[216:217], 0, s[26:27]
	s_mov_b32 m0, s42
	ds_read_b128 v[188:191], v145 offset:49152
	ds_read_b128 v[192:195], v145 offset:50176
	ds_read_b128 v[196:199], v145 offset:51200
	ds_read_b128 v[200:203], v145 offset:52224
	ds_read_b128 v[204:207], v145 offset:53248
	ds_read_b128 v[208:211], v145 offset:54272
	ds_read_b128 v[212:215], v145 offset:55296
	ds_read_b128 v[234:237], v145 offset:56320
	global_load_lds_dwordx4 v[216:217], off
	v_lshl_add_u64 v[216:217], v[222:223], 0, s[26:27]
	s_add_i32 m0, s42, 0x2000
	s_add_i32 s42, s92, s9
	global_load_lds_dwordx4 v[216:217], off
	v_lshl_add_u64 v[216:217], v[224:225], 0, s[26:27]
	s_mov_b32 m0, s42
	s_nop 0
	global_load_lds_dwordx4 v[216:217], off
	v_lshl_add_u64 v[216:217], v[226:227], 0, s[26:27]
	s_add_i32 m0, s42, 0x2000
	s_nop 0
	global_load_lds_dwordx4 v[216:217], off
	v_lshl_add_u64 v[216:217], v[238:239], 0, s[26:27]
	s_mov_b32 m0, s28
	s_nop 0
	global_load_lds_dwordx4 v[216:217], off nt
	v_lshl_add_u64 v[216:217], v[240:241], 0, s[26:27]
	s_mov_b32 m0, s29
	s_nop 0
	global_load_lds_dwordx4 v[216:217], off nt
	s_waitcnt vmcnt(8)
	s_waitcnt lgkmcnt(0)
	s_barrier
	s_setprio 1
	s_waitcnt lgkmcnt(0)
	v_mfma_f32_16x16x32_bf16 v[62:65], v[138:141], v[188:191], v[62:65]
	v_mfma_f32_16x16x32_bf16 v[58:61], v[150:153], v[188:191], v[58:61]
	v_mfma_f32_16x16x32_bf16 v[50:53], v[138:141], v[196:199], v[50:53]
	v_mfma_f32_16x16x32_bf16 v[42:45], v[150:153], v[196:199], v[42:45]
	v_mfma_f32_16x16x32_bf16 v[34:37], v[138:141], v[204:207], v[34:37]
	v_mfma_f32_16x16x32_bf16 v[26:29], v[150:153], v[204:207], v[26:29]
	v_mfma_f32_16x16x32_bf16 v[18:21], v[138:141], v[212:215], v[18:21]
	v_mfma_f32_16x16x32_bf16 v[10:13], v[150:153], v[212:215], v[10:13]
	v_mfma_f32_16x16x32_bf16 v[62:65], v[146:149], v[192:195], v[62:65]
	v_mfma_f32_16x16x32_bf16 v[58:61], v[168:171], v[192:195], v[58:61]
	v_mfma_f32_16x16x32_bf16 v[50:53], v[146:149], v[200:203], v[50:53]
	v_mfma_f32_16x16x32_bf16 v[42:45], v[168:171], v[200:203], v[42:45]
	v_mfma_f32_16x16x32_bf16 v[34:37], v[146:149], v[208:211], v[34:37]
	v_mfma_f32_16x16x32_bf16 v[26:29], v[168:171], v[208:211], v[26:29]
	v_mfma_f32_16x16x32_bf16 v[18:21], v[146:149], v[234:237], v[18:21]
	v_mfma_f32_16x16x32_bf16 v[10:13], v[168:171], v[234:237], v[10:13]
	s_setprio 0
	s_setprio 1
	v_mfma_f32_16x16x32_bf16 v[54:57], v[172:175], v[188:191], v[54:57]
	v_mfma_f32_16x16x32_bf16 v[46:49], v[180:183], v[188:191], v[46:49]
	v_mfma_f32_16x16x32_bf16 v[38:41], v[172:175], v[196:199], v[38:41]
	v_mfma_f32_16x16x32_bf16 v[30:33], v[180:183], v[196:199], v[30:33]
	v_mfma_f32_16x16x32_bf16 v[22:25], v[172:175], v[204:207], v[22:25]
	v_mfma_f32_16x16x32_bf16 v[14:17], v[180:183], v[204:207], v[14:17]
	v_mfma_f32_16x16x32_bf16 v[6:9], v[172:175], v[212:215], v[6:9]
	v_mfma_f32_16x16x32_bf16 v[2:5], v[180:183], v[212:215], v[2:5]
	v_mfma_f32_16x16x32_bf16 v[54:57], v[176:179], v[192:195], v[54:57]
	v_mfma_f32_16x16x32_bf16 v[46:49], v[184:187], v[192:195], v[46:49]
	v_mfma_f32_16x16x32_bf16 v[38:41], v[176:179], v[200:203], v[38:41]
	v_mfma_f32_16x16x32_bf16 v[30:33], v[184:187], v[200:203], v[30:33]
	v_mfma_f32_16x16x32_bf16 v[22:25], v[176:179], v[208:211], v[22:25]
	v_mfma_f32_16x16x32_bf16 v[14:17], v[184:187], v[208:211], v[14:17]
	v_mfma_f32_16x16x32_bf16 v[6:9], v[176:179], v[234:237], v[6:9]
	v_mfma_f32_16x16x32_bf16 v[2:5], v[184:187], v[234:237], v[2:5]
	s_setprio 0
	s_barrier
	s_add_u32 s40, s40, 0x100
	s_addc_u32 s41, s41, 0
	s_add_u32 s25, s25, 0x100
	s_addc_u32 s31, s31, 0
	s_cmp_ge_u32 s50, s20
	s_mov_b32 s42, s50
	s_cbranch_scc0 .LBB0_516
	s_and_b64 vcc, exec, s[22:23]
	s_cbranch_vccz .LBB0_519
	s_barrier
